# v28 with the unused in-loop skip branches removed from the full-tile K-loop
# speedup vs baseline: 1.0073x; 1.0064x over previous
.LBB0_374:
	s_add_u32 s10, s30, 0xfff80080
	s_addc_u32 s11, s31, -1
	s_add_i32 s12, 0, 0x10000
	s_cmp_eq_u32 s9, 28
	s_cselect_b32 s65, s1, s11
	s_cselect_b32 s64, s4, s10
	s_cselect_b32 s63, s5, s8
	s_cselect_b32 s62, s6, s7
	s_add_i32 s13, 0, 0x14000
	v_add_u32_e32 v142, s12, v196
	v_add_u32_e32 v158, s13, v196
	ds_read_b128 v[130:133], v142
	ds_read_b128 v[134:137], v142 offset:1024
	ds_read_b128 v[138:141], v142 offset:2048
	ds_read_b128 v[142:145], v142 offset:3072
	ds_read_b128 v[146:149], v158
	ds_read_b128 v[150:153], v158 offset:1024
	ds_read_b128 v[154:157], v158 offset:2048
	ds_read_b128 v[158:161], v158 offset:3072
	v_lshl_add_u64 v[194:195], s[30:31], 0, v[180:181]
	s_add_i32 m0, s69, 0xc000
	ds_read_b128 v[162:165], v199
	ds_read_b128 v[166:169], v199 offset:1024
	ds_read_b128 v[170:173], v199 offset:2048
	ds_read_b128 v[190:193], v199 offset:3072
	ds_read_b128 v[202:205], v199 offset:4096
	ds_read_b128 v[224:227], v199 offset:5120
	ds_read_b128 v[228:231], v199 offset:6144
	ds_read_b128 v[232:235], v199 offset:7168
	global_load_lds_dwordx4 v[194:195], off
	v_lshl_add_u64 v[194:195], s[30:31], 0, v[188:189]
	s_add_i32 m0, s69, 0xe000
	s_nop 0
	global_load_lds_dwordx4 v[194:195], off
	s_waitcnt vmcnt(8)
	s_waitcnt lgkmcnt(0)
	s_barrier
	s_setprio 1
	s_waitcnt lgkmcnt(0)
	v_mfma_f32_16x16x32_bf16 v[126:129], v[130:133], v[162:165], v[126:129]
	v_mfma_f32_16x16x32_bf16 v[122:125], v[138:141], v[162:165], v[122:125]
	v_mfma_f32_16x16x32_bf16 v[110:113], v[130:133], v[170:173], v[110:113]
	v_mfma_f32_16x16x32_bf16 v[106:109], v[138:141], v[170:173], v[106:109]
	v_mfma_f32_16x16x32_bf16 v[94:97], v[130:133], v[202:205], v[94:97]
	v_mfma_f32_16x16x32_bf16 v[90:93], v[138:141], v[202:205], v[90:93]
	v_mfma_f32_16x16x32_bf16 v[76:79], v[130:133], v[228:231], v[76:79]
	v_mfma_f32_16x16x32_bf16 v[72:75], v[138:141], v[228:231], v[72:75]
	v_mfma_f32_16x16x32_bf16 v[126:129], v[134:137], v[166:169], v[126:129]
	v_mfma_f32_16x16x32_bf16 v[122:125], v[142:145], v[166:169], v[122:125]
	v_mfma_f32_16x16x32_bf16 v[110:113], v[134:137], v[190:193], v[110:113]
	v_mfma_f32_16x16x32_bf16 v[106:109], v[142:145], v[190:193], v[106:109]
	v_mfma_f32_16x16x32_bf16 v[94:97], v[134:137], v[224:227], v[94:97]
	v_mfma_f32_16x16x32_bf16 v[90:93], v[142:145], v[224:227], v[90:93]
	v_mfma_f32_16x16x32_bf16 v[76:79], v[134:137], v[232:235], v[76:79]
	v_mfma_f32_16x16x32_bf16 v[72:75], v[142:145], v[232:235], v[72:75]
	s_setprio 0
	s_setprio 1
	v_mfma_f32_16x16x32_bf16 v[118:121], v[146:149], v[162:165], v[118:121]
	v_mfma_f32_16x16x32_bf16 v[114:117], v[154:157], v[162:165], v[114:117]
	v_mfma_f32_16x16x32_bf16 v[102:105], v[146:149], v[170:173], v[102:105]
	v_mfma_f32_16x16x32_bf16 v[98:101], v[154:157], v[170:173], v[98:101]
	v_mfma_f32_16x16x32_bf16 v[86:89], v[146:149], v[202:205], v[86:89]
	v_mfma_f32_16x16x32_bf16 v[80:83], v[154:157], v[202:205], v[80:83]
	v_mfma_f32_16x16x32_bf16 v[68:71], v[146:149], v[228:231], v[68:71]
	v_mfma_f32_16x16x32_bf16 v[64:67], v[154:157], v[228:231], v[64:67]
	v_mfma_f32_16x16x32_bf16 v[118:121], v[150:153], v[166:169], v[118:121]
	v_mfma_f32_16x16x32_bf16 v[114:117], v[158:161], v[166:169], v[114:117]
	v_mfma_f32_16x16x32_bf16 v[102:105], v[150:153], v[190:193], v[102:105]
	v_mfma_f32_16x16x32_bf16 v[98:101], v[158:161], v[190:193], v[98:101]
	v_mfma_f32_16x16x32_bf16 v[86:89], v[150:153], v[224:227], v[86:89]
	v_mfma_f32_16x16x32_bf16 v[80:83], v[158:161], v[224:227], v[80:83]
	v_mfma_f32_16x16x32_bf16 v[68:71], v[150:153], v[232:235], v[68:71]
	v_mfma_f32_16x16x32_bf16 v[64:67], v[158:161], v[232:235], v[64:67]
	s_setprio 0
	s_barrier
	s_add_i32 s10, s12, s66
	v_lshl_add_u64 v[194:195], s[62:63], 0, v[84:85]
	s_mov_b32 m0, s10
	ds_read_b128 v[162:165], v199 offset:16384
	ds_read_b128 v[166:169], v199 offset:17408
	ds_read_b128 v[170:173], v199 offset:18432
	ds_read_b128 v[190:193], v199 offset:19456
	ds_read_b128 v[202:205], v199 offset:20480
	ds_read_b128 v[224:227], v199 offset:21504
	ds_read_b128 v[228:231], v199 offset:22528
	ds_read_b128 v[232:235], v199 offset:23552
	global_load_lds_dwordx4 v[194:195], off
	s_add_i32 m0, s10, 0x2000
	s_add_u32 s10, s62, 0x80000
	v_lshl_add_u64 v[236:237], s[62:63], 0, v[178:179]
	s_addc_u32 s11, s63, 0
	s_add_i32 s12, s13, s66
	global_load_lds_dwordx4 v[236:237], off
	v_lshl_add_u64 v[238:239], s[10:11], 0, v[84:85]
	s_mov_b32 m0, s12
	v_lshl_add_u64 v[240:241], s[64:65], 0, v[176:177]
	global_load_lds_dwordx4 v[238:239], off
	v_lshl_add_u64 v[238:239], s[10:11], 0, v[178:179]
	s_add_i32 m0, s12, 0x2000
	s_nop 0
	global_load_lds_dwordx4 v[238:239], off
	v_lshl_add_u64 v[238:239], s[64:65], 0, v[174:175]
	s_mov_b32 m0, s69
	s_nop 0
	global_load_lds_dwordx4 v[238:239], off
	s_mov_b32 m0, s70
	s_nop 0
	global_load_lds_dwordx4 v[240:241], off
	s_waitcnt vmcnt(8)
	s_waitcnt lgkmcnt(0)
	s_barrier
	s_setprio 1
	s_waitcnt lgkmcnt(0)
	v_mfma_f32_16x16x32_bf16 v[60:63], v[130:133], v[162:165], v[60:63]
	v_mfma_f32_16x16x32_bf16 v[56:59], v[138:141], v[162:165], v[56:59]
	v_mfma_f32_16x16x32_bf16 v[44:47], v[130:133], v[170:173], v[44:47]
	v_mfma_f32_16x16x32_bf16 v[40:43], v[138:141], v[170:173], v[40:43]
	v_mfma_f32_16x16x32_bf16 v[28:31], v[130:133], v[202:205], v[28:31]
	v_mfma_f32_16x16x32_bf16 v[24:27], v[138:141], v[202:205], v[24:27]
	v_mfma_f32_16x16x32_bf16 v[12:15], v[130:133], v[228:231], v[12:15]
	v_mfma_f32_16x16x32_bf16 v[8:11], v[138:141], v[228:231], v[8:11]
	v_mfma_f32_16x16x32_bf16 v[60:63], v[134:137], v[166:169], v[60:63]
	v_mfma_f32_16x16x32_bf16 v[56:59], v[142:145], v[166:169], v[56:59]
	v_mfma_f32_16x16x32_bf16 v[44:47], v[134:137], v[190:193], v[44:47]
	v_mfma_f32_16x16x32_bf16 v[40:43], v[142:145], v[190:193], v[40:43]
	v_mfma_f32_16x16x32_bf16 v[28:31], v[134:137], v[224:227], v[28:31]
	v_mfma_f32_16x16x32_bf16 v[24:27], v[142:145], v[224:227], v[24:27]
	v_mfma_f32_16x16x32_bf16 v[12:15], v[134:137], v[232:235], v[12:15]
	v_mfma_f32_16x16x32_bf16 v[8:11], v[142:145], v[232:235], v[8:11]
	s_setprio 0
	s_setprio 1
	v_mfma_f32_16x16x32_bf16 v[52:55], v[146:149], v[162:165], v[52:55]
	v_mfma_f32_16x16x32_bf16 v[48:51], v[154:157], v[162:165], v[48:51]
	v_mfma_f32_16x16x32_bf16 v[36:39], v[146:149], v[170:173], v[36:39]
	v_mfma_f32_16x16x32_bf16 v[32:35], v[154:157], v[170:173], v[32:35]
	v_mfma_f32_16x16x32_bf16 v[20:23], v[146:149], v[202:205], v[20:23]
	v_mfma_f32_16x16x32_bf16 v[16:19], v[154:157], v[202:205], v[16:19]
	v_mfma_f32_16x16x32_bf16 v[4:7], v[146:149], v[228:231], v[4:7]
	v_mfma_f32_16x16x32_bf16 v[0:3], v[154:157], v[228:231], v[0:3]
	v_mfma_f32_16x16x32_bf16 v[52:55], v[150:153], v[166:169], v[52:55]
	v_mfma_f32_16x16x32_bf16 v[48:51], v[158:161], v[166:169], v[48:51]
	v_mfma_f32_16x16x32_bf16 v[36:39], v[150:153], v[190:193], v[36:39]
	v_mfma_f32_16x16x32_bf16 v[32:35], v[158:161], v[190:193], v[32:35]
	v_mfma_f32_16x16x32_bf16 v[20:23], v[150:153], v[224:227], v[20:23]
	v_mfma_f32_16x16x32_bf16 v[16:19], v[158:161], v[224:227], v[16:19]
	v_mfma_f32_16x16x32_bf16 v[4:7], v[150:153], v[232:235], v[4:7]
	v_mfma_f32_16x16x32_bf16 v[0:3], v[158:161], v[232:235], v[0:3]
	s_setprio 0
	s_barrier
	s_add_i32 s12, 0, 0x18000
	s_add_i32 s13, 0, 0x1c000
	v_add_u32_e32 v142, s12, v196
	v_add_u32_e32 v158, s13, v196
	ds_read_b128 v[130:133], v142
	ds_read_b128 v[134:137], v142 offset:1024
	ds_read_b128 v[138:141], v142 offset:2048
	ds_read_b128 v[142:145], v142 offset:3072
	ds_read_b128 v[146:149], v158
	ds_read_b128 v[150:153], v158 offset:1024
	ds_read_b128 v[154:157], v158 offset:2048
	ds_read_b128 v[158:161], v158 offset:3072
	s_add_u32 s10, s64, 0x80000
	s_addc_u32 s11, s65, 0
	s_mov_b32 m0, s71
	v_lshl_add_u64 v[242:243], s[10:11], 0, v[174:175]
	ds_read_b128 v[162:165], v199 offset:32768
	ds_read_b128 v[166:169], v199 offset:33792
	ds_read_b128 v[170:173], v199 offset:34816
	ds_read_b128 v[190:193], v199 offset:35840
	ds_read_b128 v[202:205], v199 offset:36864
	ds_read_b128 v[224:227], v199 offset:37888
	ds_read_b128 v[228:231], v199 offset:38912
	ds_read_b128 v[232:235], v199 offset:39936
	global_load_lds_dwordx4 v[242:243], off
	v_lshl_add_u64 v[242:243], s[10:11], 0, v[176:177]
	s_mov_b32 m0, s72
	s_nop 0
	global_load_lds_dwordx4 v[242:243], off
	s_waitcnt vmcnt(8)
	s_waitcnt lgkmcnt(0)
	s_barrier
	s_setprio 1
	s_waitcnt lgkmcnt(0)
	v_mfma_f32_16x16x32_bf16 v[126:129], v[130:133], v[162:165], v[126:129]
	v_mfma_f32_16x16x32_bf16 v[122:125], v[138:141], v[162:165], v[122:125]
	v_mfma_f32_16x16x32_bf16 v[110:113], v[130:133], v[170:173], v[110:113]
	v_mfma_f32_16x16x32_bf16 v[106:109], v[138:141], v[170:173], v[106:109]
	v_mfma_f32_16x16x32_bf16 v[94:97], v[130:133], v[202:205], v[94:97]
	v_mfma_f32_16x16x32_bf16 v[90:93], v[138:141], v[202:205], v[90:93]
	v_mfma_f32_16x16x32_bf16 v[76:79], v[130:133], v[228:231], v[76:79]
	v_mfma_f32_16x16x32_bf16 v[72:75], v[138:141], v[228:231], v[72:75]
	v_mfma_f32_16x16x32_bf16 v[126:129], v[134:137], v[166:169], v[126:129]
	v_mfma_f32_16x16x32_bf16 v[122:125], v[142:145], v[166:169], v[122:125]
	v_mfma_f32_16x16x32_bf16 v[110:113], v[134:137], v[190:193], v[110:113]
	v_mfma_f32_16x16x32_bf16 v[106:109], v[142:145], v[190:193], v[106:109]
	v_mfma_f32_16x16x32_bf16 v[94:97], v[134:137], v[224:227], v[94:97]
	v_mfma_f32_16x16x32_bf16 v[90:93], v[142:145], v[224:227], v[90:93]
	v_mfma_f32_16x16x32_bf16 v[76:79], v[134:137], v[232:235], v[76:79]
	v_mfma_f32_16x16x32_bf16 v[72:75], v[142:145], v[232:235], v[72:75]
	s_setprio 0
	s_setprio 1
	v_mfma_f32_16x16x32_bf16 v[118:121], v[146:149], v[162:165], v[118:121]
	v_mfma_f32_16x16x32_bf16 v[114:117], v[154:157], v[162:165], v[114:117]
	v_mfma_f32_16x16x32_bf16 v[102:105], v[146:149], v[170:173], v[102:105]
	v_mfma_f32_16x16x32_bf16 v[98:101], v[154:157], v[170:173], v[98:101]
	v_mfma_f32_16x16x32_bf16 v[86:89], v[146:149], v[202:205], v[86:89]
	v_mfma_f32_16x16x32_bf16 v[80:83], v[154:157], v[202:205], v[80:83]
	v_mfma_f32_16x16x32_bf16 v[68:71], v[146:149], v[228:231], v[68:71]
	v_mfma_f32_16x16x32_bf16 v[64:67], v[154:157], v[228:231], v[64:67]
	v_mfma_f32_16x16x32_bf16 v[118:121], v[150:153], v[166:169], v[118:121]
	v_mfma_f32_16x16x32_bf16 v[114:117], v[158:161], v[166:169], v[114:117]
	v_mfma_f32_16x16x32_bf16 v[102:105], v[150:153], v[190:193], v[102:105]
	v_mfma_f32_16x16x32_bf16 v[98:101], v[158:161], v[190:193], v[98:101]
	v_mfma_f32_16x16x32_bf16 v[86:89], v[150:153], v[224:227], v[86:89]
	v_mfma_f32_16x16x32_bf16 v[80:83], v[158:161], v[224:227], v[80:83]
	v_mfma_f32_16x16x32_bf16 v[68:71], v[150:153], v[232:235], v[68:71]
	v_mfma_f32_16x16x32_bf16 v[64:67], v[158:161], v[232:235], v[64:67]
	s_setprio 0
	s_barrier
	s_add_i32 s10, s12, s66
	v_lshl_add_u64 v[194:195], v[194:195], 0, s[2:3]
	s_mov_b32 m0, s10
	ds_read_b128 v[162:165], v199 offset:49152
	ds_read_b128 v[166:169], v199 offset:50176
	ds_read_b128 v[170:173], v199 offset:51200
	ds_read_b128 v[190:193], v199 offset:52224
	ds_read_b128 v[202:205], v199 offset:53248
	ds_read_b128 v[224:227], v199 offset:54272
	ds_read_b128 v[228:231], v199 offset:55296
	ds_read_b128 v[232:235], v199 offset:56320
	global_load_lds_dwordx4 v[194:195], off
	s_add_i32 m0, s10, 0x2000
	s_add_u32 s10, s62, 0x80080
	v_lshl_add_u64 v[194:195], v[236:237], 0, s[2:3]
	s_addc_u32 s11, s63, 0
	s_add_i32 s12, s13, s66
	global_load_lds_dwordx4 v[194:195], off
	v_lshl_add_u64 v[194:195], s[10:11], 0, v[84:85]
	s_mov_b32 m0, s12
	s_nop 0
	global_load_lds_dwordx4 v[194:195], off
	v_lshl_add_u64 v[194:195], s[10:11], 0, v[178:179]
	s_add_i32 m0, s12, 0x2000
	s_nop 0
	global_load_lds_dwordx4 v[194:195], off
	v_lshl_add_u64 v[194:195], v[238:239], 0, s[2:3]
	s_mov_b32 m0, s74
	s_nop 0
	global_load_lds_dwordx4 v[194:195], off
	v_lshl_add_u64 v[194:195], v[240:241], 0, s[2:3]
	s_mov_b32 m0, s75
	s_nop 0
	global_load_lds_dwordx4 v[194:195], off
	s_waitcnt vmcnt(8)
	s_waitcnt lgkmcnt(0)
	s_barrier
	s_setprio 1
	s_waitcnt lgkmcnt(0)
	v_mfma_f32_16x16x32_bf16 v[60:63], v[130:133], v[162:165], v[60:63]
	v_mfma_f32_16x16x32_bf16 v[56:59], v[138:141], v[162:165], v[56:59]
	v_mfma_f32_16x16x32_bf16 v[44:47], v[130:133], v[170:173], v[44:47]
	v_mfma_f32_16x16x32_bf16 v[40:43], v[138:141], v[170:173], v[40:43]
	v_mfma_f32_16x16x32_bf16 v[28:31], v[130:133], v[202:205], v[28:31]
	v_mfma_f32_16x16x32_bf16 v[24:27], v[138:141], v[202:205], v[24:27]
	v_mfma_f32_16x16x32_bf16 v[12:15], v[130:133], v[228:231], v[12:15]
	v_mfma_f32_16x16x32_bf16 v[8:11], v[138:141], v[228:231], v[8:11]
	v_mfma_f32_16x16x32_bf16 v[60:63], v[134:137], v[166:169], v[60:63]
	v_mfma_f32_16x16x32_bf16 v[56:59], v[142:145], v[166:169], v[56:59]
	v_mfma_f32_16x16x32_bf16 v[44:47], v[134:137], v[190:193], v[44:47]
	v_mfma_f32_16x16x32_bf16 v[40:43], v[142:145], v[190:193], v[40:43]
	v_mfma_f32_16x16x32_bf16 v[28:31], v[134:137], v[224:227], v[28:31]
	v_mfma_f32_16x16x32_bf16 v[24:27], v[142:145], v[224:227], v[24:27]
	v_mfma_f32_16x16x32_bf16 v[12:15], v[134:137], v[232:235], v[12:15]
	v_mfma_f32_16x16x32_bf16 v[8:11], v[142:145], v[232:235], v[8:11]
	s_setprio 0
	s_setprio 1
	v_mfma_f32_16x16x32_bf16 v[52:55], v[146:149], v[162:165], v[52:55]
	v_mfma_f32_16x16x32_bf16 v[48:51], v[154:157], v[162:165], v[48:51]
	v_mfma_f32_16x16x32_bf16 v[36:39], v[146:149], v[170:173], v[36:39]
	v_mfma_f32_16x16x32_bf16 v[32:35], v[154:157], v[170:173], v[32:35]
	v_mfma_f32_16x16x32_bf16 v[20:23], v[146:149], v[202:205], v[20:23]
	v_mfma_f32_16x16x32_bf16 v[16:19], v[154:157], v[202:205], v[16:19]
	v_mfma_f32_16x16x32_bf16 v[4:7], v[146:149], v[228:231], v[4:7]
	v_mfma_f32_16x16x32_bf16 v[0:3], v[154:157], v[228:231], v[0:3]
	v_mfma_f32_16x16x32_bf16 v[52:55], v[150:153], v[166:169], v[52:55]
	v_mfma_f32_16x16x32_bf16 v[48:51], v[158:161], v[166:169], v[48:51]
	v_mfma_f32_16x16x32_bf16 v[36:39], v[150:153], v[190:193], v[36:39]
	v_mfma_f32_16x16x32_bf16 v[32:35], v[158:161], v[190:193], v[32:35]
	v_mfma_f32_16x16x32_bf16 v[20:23], v[150:153], v[224:227], v[20:23]
	v_mfma_f32_16x16x32_bf16 v[16:19], v[158:161], v[224:227], v[16:19]
	v_mfma_f32_16x16x32_bf16 v[4:7], v[150:153], v[232:235], v[4:7]
	v_mfma_f32_16x16x32_bf16 v[0:3], v[158:161], v[232:235], v[0:3]
	s_setprio 0
	s_barrier
	s_add_i32 s9, s9, 2
	s_add_u32 s30, s30, 0x100
	s_addc_u32 s31, s31, 0
	s_add_u32 s7, s7, 0x100
	s_addc_u32 s8, s8, 0
	s_cmp_gt_u32 s9, 29
	s_cbranch_scc0 .LBB0_374
